# N1 + producing wave requests its P fragments and first transpose-read group from inside the softmax instead of at the head of the interval
# speedup vs baseline: 1.0173x; 1.0019x over previous
; #define SBAR() __builtin_amdgcn_sched_barrier(0)
; __device__ __forceinline__ void partialSM(f32x16& p0, f32x16& p1, float& m_reg, float& mn, float& alpha) {
;   constexpr float C = SCALE * 1.4426950408889634f;
;   float pmax = p0[0]; for (int r = 1; r < 16; ++r) pmax = fmaxf(pmax, p0[r]); for (int r = 0; r < 16; ++r) pmax = fmaxf(pmax, p1[r]);
;   { auto rr = __builtin_amdgcn_permlane32_swap(__float_as_uint(pmax), __float_as_uint(pmax), false, false);
;     pmax = fmaxf(__uint_as_float(rr[0]), __uint_as_float(rr[1])); }
;   if (__builtin_expect(__all(pmax - m_reg <= THR / SCALE), 1)) { mn = m_reg; alpha = 1.f; }
;   else { mn = fmaxf(m_reg, pmax); alpha = __builtin_amdgcn_exp2f((m_reg - mn) * C); m_reg = mn; }
;   float mnC = -mn * C;
; template <int LDQ, int LDK, int LDO>
; __device__ __forceinline__ void attn_pair_body(const bf16* __restrict__ Qb, const bf16* __restrict__ Kh, const bf16* __restrict__ Vh, float* __restrict__ Ob, int NT, char* lds, int tid_in) {
;     ...
;     const bool flp = (j >= 1) && (__builtin_amdgcn_readfirstlane((int)FLp[pb]) != 0);
;     const float alp_v = ALp[pb * 32 + r32], m_v = Mp[r32];
;     const bf16x8 a0 = *reinterpret_cast<const bf16x8*>(Pp + pb * 4096 + 0 * 1024 + lane * 16), a1 = *reinterpret_cast<const bf16x8*>(Pp + pb * 4096 + 1 * 1024 + lane * 16);
;     const bf16x8 a2 = *reinterpret_cast<const bf16x8*>(Pp + pb * 4096 + 2 * 1024 + lane * 16), a3 = *reinterpret_cast<const bf16x8*>(Pp + pb * 4096 + 3 * 1024 + lane * 16);
;     SBAR();
;     KWRITE(b);
;     VWRITE(b);
;     { const int tk = j + 3 < NT ? j + 3 : NT - 1, tv = j + 1 < NT ? j + 1 : NT - 1; KLOAD(tk * KVBLK); VLOAD(tv * KVBLK); }
;     SBAR();
;     if (prod) {
;       if (flp) l_reg *= alp_v;
;       if (j >= 1) m_reg = m_v;
;       float mn, al; bf16x8 pa0, pa1, pa2, pa3;
;       partialSM(p0, p1, m_reg, mn, al);
;       finishSM(p0, p1, al, l_reg, pa0, pa1, pa2, pa3);
;       *reinterpret_cast<bf16x8*>(Pp + b * 4096 + 0 * 1024 + lane * 16) = pa0; *reinterpret_cast<bf16x8*>(Pp + b * 4096 + 1 * 1024 + lane * 16) = pa1;
;       *reinterpret_cast<bf16x8*>(Pp + b * 4096 + 2 * 1024 + lane * 16) = pa2; *reinterpret_cast<bf16x8*>(Pp + b * 4096 + 3 * 1024 + lane * 16) = pa3;
;       if (hi == 0) { ALp[b * 32 + r32] = al; Mp[r32] = m_reg; }
;       const unsigned fl = __any(al < 1.f) ? 1u : 0u;
;       if (lane == 0) FLp[b] = fl;
.LBB0_1023:
	s_and_b64 vcc, exec, s[42:43]
	s_cbranch_vccnz .Lpa_cons
	v_lshl_add_u32 v156, s21, 7, v214
	ds_read_b32 v219, v156
	ds_read_b32 v220, v212
	s_xor_b32 s65, s65, 0x4000
	s_xor_b32 s77, s77, 0x8000
	s_add_u32 s74, s74, 0x90000
	s_addc_u32 s75, s75, 0
	s_add_u32 s92, s92, 0x90000
	s_addc_u32 s93, s93, 0
	s_add_u32 s96, s96, 0x90000
	s_addc_u32 s97, s97, 0
	s_mov_b32 m0, s65
	v_max_f32_e32 v176, v85, v85
	v_max_f32_e32 v177, v84, v84
	global_load_lds_dwordx4 v172, s[74:75]
	s_add_i32 m0, s65, 0x400
	v_max_f32_e32 v176, v177, v176
	v_max3_f32 v176, v176, v86, v87
	v_max3_f32 v176, v176, v88, v89
	v_max3_f32 v176, v176, v90, v91
	v_max3_f32 v176, v176, v92, v93
	v_max3_f32 v176, v176, v94, v95
	v_max3_f32 v176, v176, v96, v97
	v_max3_f32 v176, v176, v98, v99
	global_load_lds_dwordx4 v173, s[74:75]
	s_mov_b32 m0, s77
	v_max3_f32 v176, v176, v68, v69
	v_max3_f32 v176, v176, v70, v71
	v_max3_f32 v176, v176, v72, v73
	v_max3_f32 v176, v176, v74, v75
	v_max3_f32 v176, v176, v76, v77
	v_max3_f32 v176, v176, v78, v79
	v_max3_f32 v176, v176, v80, v81
	v_max3_f32 v176, v176, v82, v83
	global_load_lds_dwordx4 v174, s[92:93]
	s_add_i32 m0, s77, 0x380
	v_mov_b32_e32 v177, v176
	s_nop 1
	v_permlane32_swap_b32_e32 v176, v177
	v_max_f32_e32 v177, v177, v177
	v_max_f32_e32 v176, v176, v176
	s_waitcnt lgkmcnt(0)
	v_readfirstlane_b32 s29, v210
	s_cmp_lg_u32 s29, 0
	s_cselect_b64 s[62:63], -1, 0
	s_and_b64 s[62:63], s[62:63], s[56:57]
	v_cndmask_b32_e64 v217, v220, v217, s[44:45]
	v_max_f32_e32 v221, v176, v177
	v_sub_f32_e32 v176, v221, v217
	v_cmp_ge_f32_e32 vcc, s27, v176
	s_cmp_eq_u64 vcc, exec
	v_mov_b32_e32 v220, 1.0
	s_cbranch_scc0 .LBB0_1036
.LBB0_1025:
	v_mul_f32_e32 v176, 0xbe0293ee, v217
	v_fmamk_f32 v84, v84, 0x3e0293ee, v176
	v_fmamk_f32 v85, v85, 0x3e0293ee, v176
	v_exp_f32_e32 v84, v84
	v_fmamk_f32 v86, v86, 0x3e0293ee, v176
	v_exp_f32_e32 v85, v85
	v_fmamk_f32 v87, v87, 0x3e0293ee, v176
	v_exp_f32_e32 v86, v86
	v_fmamk_f32 v88, v88, 0x3e0293ee, v176
	v_fmamk_f32 v89, v89, 0x3e0293ee, v176
	v_fmamk_f32 v90, v90, 0x3e0293ee, v176
	v_fmamk_f32 v91, v91, 0x3e0293ee, v176
	v_fmamk_f32 v92, v92, 0x3e0293ee, v176
	global_load_lds_dwordx4 v174, s[92:93] offset:128
	s_add_i32 m0, s77, 0x800
	v_fmamk_f32 v93, v93, 0x3e0293ee, v176
	v_fmamk_f32 v94, v94, 0x3e0293ee, v176
	v_fmamk_f32 v95, v95, 0x3e0293ee, v176
	v_fmamk_f32 v96, v96, 0x3e0293ee, v176
	v_fmamk_f32 v97, v97, 0x3e0293ee, v176
	v_fmamk_f32 v98, v98, 0x3e0293ee, v176
	v_fmamk_f32 v99, v99, 0x3e0293ee, v176
	v_lshl_add_u32 v157, s21, 12, v216
	ds_read_b128 v[168:171], v157
	ds_read_b128 v[164:167], v157 offset:1024
	ds_read_b128 v[160:163], v157 offset:2048
	ds_read_b128 v[156:159], v157 offset:3072
	v_lshl_add_u32 v190, s21, 15, v211
	ds_read_b64_tr_b16 v[132:133], v190 offset:0
	ds_read_b64_tr_b16 v[134:135], v190 offset:0x800
	ds_read_b64_tr_b16 v[136:137], v190 offset:0x1000
	ds_read_b64_tr_b16 v[138:139], v190 offset:0x1800
	ds_read_b64_tr_b16 v[140:141], v190 offset:0x2000
	ds_read_b64_tr_b16 v[142:143], v190 offset:0x2800
	ds_read_b64_tr_b16 v[144:145], v190 offset:0x3000
	ds_read_b64_tr_b16 v[146:147], v190 offset:0x3800
	v_fmamk_f32 v68, v68, 0x3e0293ee, v176
	v_fmamk_f32 v69, v69, 0x3e0293ee, v176
	v_fmamk_f32 v70, v70, 0x3e0293ee, v176
	v_fmamk_f32 v71, v71, 0x3e0293ee, v176
	v_fmamk_f32 v72, v72, 0x3e0293ee, v176
	v_fmamk_f32 v73, v73, 0x3e0293ee, v176
	v_fmamk_f32 v74, v74, 0x3e0293ee, v176
	global_load_lds_dwordx4 v174, s[96:97]
	s_add_i32 m0, s77, 0xb80
	v_fmamk_f32 v75, v75, 0x3e0293ee, v176
	v_fmamk_f32 v76, v76, 0x3e0293ee, v176
	v_fmamk_f32 v77, v77, 0x3e0293ee, v176
	v_fmamk_f32 v78, v78, 0x3e0293ee, v176
	v_fmamk_f32 v79, v79, 0x3e0293ee, v176
	v_fmamk_f32 v80, v80, 0x3e0293ee, v176
	v_fmamk_f32 v81, v81, 0x3e0293ee, v176
	v_fmamk_f32 v82, v82, 0x3e0293ee, v176
	v_fmac_f32_e32 v176, 0x3e0293ee, v83
	v_exp_f32_e32 v87, v87
	v_exp_f32_e32 v88, v88
	v_exp_f32_e32 v83, v176
	v_add_f32_e32 v176, 0, v84
	v_exp_f32_e32 v89, v89
	v_add_f32_e32 v176, v85, v176
	v_exp_f32_e32 v90, v90
	global_load_lds_dwordx4 v174, s[96:97] offset:128
	v_add_f32_e32 v176, v86, v176
	v_exp_f32_e32 v91, v91
	v_add_f32_e32 v176, v87, v176
	v_exp_f32_e32 v92, v92
	v_add_f32_e32 v176, v88, v176
	v_exp_f32_e32 v93, v93
	v_add_f32_e32 v176, v89, v176
	v_exp_f32_e32 v94, v94
	v_add_f32_e32 v176, v90, v176
	v_exp_f32_e32 v95, v95
	v_add_f32_e32 v176, v91, v176
	v_exp_f32_e32 v96, v96
	v_add_f32_e32 v176, v92, v176
	v_exp_f32_e32 v97, v97
	v_add_f32_e32 v176, v93, v176
	v_exp_f32_e32 v98, v98
	v_add_f32_e32 v176, v94, v176
	v_exp_f32_e32 v99, v99
	v_add_f32_e32 v176, v95, v176
	v_exp_f32_e32 v68, v68
	v_add_f32_e32 v176, v96, v176
	v_exp_f32_e32 v69, v69
	v_add_f32_e32 v176, v97, v176
	v_exp_f32_e32 v70, v70
	v_add_f32_e32 v176, v98, v176
	v_exp_f32_e32 v71, v71
	v_add_f32_e32 v176, v99, v176
	v_exp_f32_e32 v72, v72
	v_add_f32_e32 v176, v68, v176
	v_exp_f32_e32 v73, v73
	v_add_f32_e32 v176, v69, v176
	v_exp_f32_e32 v74, v74
	v_add_f32_e32 v176, v70, v176
	v_exp_f32_e32 v75, v75
	v_add_f32_e32 v176, v71, v176
	v_exp_f32_e32 v76, v76
	v_add_f32_e32 v176, v72, v176
	v_exp_f32_e32 v77, v77
	v_add_f32_e32 v176, v73, v176
	v_exp_f32_e32 v78, v78
	v_add_f32_e32 v176, v74, v176
	v_exp_f32_e32 v79, v79
	v_add_f32_e32 v176, v75, v176
	v_exp_f32_e32 v80, v80
	v_add_f32_e32 v176, v76, v176
	v_exp_f32_e32 v81, v81
	v_add_f32_e32 v176, v77, v176
	v_exp_f32_e32 v82, v82
	v_add_f32_e32 v176, v78, v176
	v_add_f32_e32 v176, v79, v176
	v_add_f32_e32 v176, v80, v176
	v_add_f32_e32 v176, v81, v176
	v_add_f32_e32 v176, v82, v176
	v_add_f32_e32 v221, v83, v176
	v_mov_b32_e32 v222, v221
	v_cvt_pk_bf16_f32 v224, v84, v85
	v_cvt_pk_bf16_f32 v225, v86, v87
	v_cvt_pk_bf16_f32 v226, v88, v89
	v_cvt_pk_bf16_f32 v227, v90, v91
	s_nop 1
	v_permlane32_swap_b32_e32 v221, v222
	v_permlane32_swap_b32_e32 v224, v226
	v_permlane32_swap_b32_e32 v225, v227
	v_cvt_pk_bf16_f32 v234, v92, v93
	v_cvt_pk_bf16_f32 v235, v94, v95
	v_cvt_pk_bf16_f32 v236, v96, v97
	v_cvt_pk_bf16_f32 v237, v98, v99
	v_cvt_pk_bf16_f32 v238, v68, v69
	v_cvt_pk_bf16_f32 v239, v70, v71
	v_cvt_pk_bf16_f32 v240, v72, v73
	v_cvt_pk_bf16_f32 v241, v74, v75
	v_cvt_pk_bf16_f32 v242, v76, v77
	v_cvt_pk_bf16_f32 v243, v78, v79
	v_cvt_pk_bf16_f32 v244, v80, v81
	v_cvt_pk_bf16_f32 v245, v82, v83
	v_add_u32_e32 v176, s13, v203
	v_permlane32_swap_b32_e32 v234, v236
	v_permlane32_swap_b32_e32 v235, v237
	v_permlane32_swap_b32_e32 v238, v240
	v_permlane32_swap_b32_e32 v239, v241
	v_permlane32_swap_b32_e32 v242, v244
	v_permlane32_swap_b32_e32 v243, v245
	ds_write_b128 v176, v[224:227]
	ds_write_b128 v176, v[234:237] offset:1024
	ds_write_b128 v176, v[238:241] offset:2048
	ds_write_b128 v176, v[242:245] offset:3072
	s_and_saveexec_b64 s[42:43], s[38:39]
	s_cbranch_execz .LBB0_1027
	ds_write_b32 v213, v220
	ds_write_b32 v212, v217

; #define SBAR() __builtin_amdgcn_sched_barrier(0)
; __device__ __forceinline__ int crow(int r, int hi) { return (r & 3) + 8 * (r >> 2) + 4 * hi; }
; #define KLOAD(k0) do { ks0 = *reinterpret_cast<const bf16x8*>(&Kh[(long)((k0) + sr) * LDK + sc]); ks1 = *reinterpret_cast<const bf16x8*>(&Kh[(long)((k0) + 32 + sr) * LDK + sc]); } while (0)
; template <int LDQ, int LDK, int LDO>
; __device__ __forceinline__ void attn_pair_body(const bf16* __restrict__ Qb, const bf16* __restrict__ Kh, const bf16* __restrict__ Vh, float* __restrict__ Ob, int NT, char* lds, int tid_in) {
;     ...
;     const float alp_v = ALp[pb * 32 + r32], m_v = Mp[r32];
;     const bf16x8 a0 = *reinterpret_cast<const bf16x8*>(Pp + pb * 4096 + 0 * 1024 + lane * 16), a1 = *reinterpret_cast<const bf16x8*>(Pp + pb * 4096 + 1 * 1024 + lane * 16);
;     const bf16x8 a2 = *reinterpret_cast<const bf16x8*>(Pp + pb * 4096 + 2 * 1024 + lane * 16), a3 = *reinterpret_cast<const bf16x8*>(Pp + pb * 4096 + 3 * 1024 + lane * 16);
;     SBAR();
;     KWRITE(b);
;     VWRITE(b);
;     { const int tk = j + 3 < NT ? j + 3 : NT - 1, tv = j + 1 < NT ? j + 1 : NT - 1; KLOAD(tk * KVBLK); VLOAD(tv * KVBLK); }
;     SBAR();
;     if (prod) {
;       if (flp) l_reg *= alp_v;
;       if (j >= 1) m_reg = m_v;
;       float mn, al; bf16x8 pa0, pa1, pa2, pa3;
;       partialSM(p0, p1, m_reg, mn, al);
;       finishSM(p0, p1, al, l_reg, pa0, pa1, pa2, pa3);
;       *reinterpret_cast<bf16x8*>(Pp + b * 4096 + 0 * 1024 + lane * 16) = pa0; *reinterpret_cast<bf16x8*>(Pp + b * 4096 + 1 * 1024 + lane * 16) = pa1;
;       *reinterpret_cast<bf16x8*>(Pp + b * 4096 + 2 * 1024 + lane * 16) = pa2; *reinterpret_cast<bf16x8*>(Pp + b * 4096 + 3 * 1024 + lane * 16) = pa3;
;       if (hi == 0) { ALp[b * 32 + r32] = al; Mp[r32] = m_reg; }
;       const unsigned fl = __any(al < 1.f) ? 1u : 0u;
;       if (lane == 0) FLp[b] = fl;
;       SBAR();
;     }
;     if (j >= 1) {
;       if (flp) {
; #pragma unroll
;         for (int d = 0; d < 4; ++d)
; #pragma unroll
;           for (int r = 0; r < 16; ++r) o[d][r] *= ALp[pb * 32 + crow(r, hi)];
;       }
;       pv_batched(o, vb0 + pb * 32768, a0, a1, a2, a3);
;     }
;     if (!prod && j + 1 < NT) { SBAR(); qkt_batched(p0, p1, (const bf16*)(K_lds + pb * 16384), qr, r32, hi); SBAR(); }
.Lpa_cons:
	v_lshl_add_u32 v157, s21, 12, v216
	ds_read_b128 v[168:171], v157
	ds_read_b128 v[164:167], v157 offset:1024
	ds_read_b128 v[160:163], v157 offset:2048
	ds_read_b128 v[156:159], v157 offset:3072
	s_waitcnt lgkmcnt(4)
	v_readfirstlane_b32 s29, v210
	s_cmp_lg_u32 s29, 0
	s_cselect_b64 s[62:63], -1, 0
	s_and_b64 s[62:63], s[62:63], s[56:57]
	s_lshl_b32 s94, s21, 14
	s_add_i32 s94, s94, 0x10000
	v_add3_u32 v176, s94, v194, v192
	ds_read_b128 v[132:135], v176
	ds_read_b128 v[136:139], v176 offset:8192
	v_add3_u32 v176, s94, v193, v192
	ds_read_b128 v[140:143], v176
	ds_read_b128 v[144:147], v176 offset:8192
	v_add3_u32 v176, s94, v195, v192
	ds_read_b128 v[148:151], v176
	ds_read_b128 v[152:155], v176 offset:8192
	s_andn2_b64 vcc, exec, s[56:57]
	s_cbranch_vccnz .Lpa_cons_j0
	s_lshl_b32 s28, s21, 5
	s_andn2_b64 vcc, exec, s[62:63]
	s_cbranch_vccnz .Lpa_cons_pv
	v_lshl_add_u32 v176, s28, 2, v215
	ds_read_b128 v[220:223], v176 offset:96
	ds_read_b128 v[224:227], v176 offset:64
	ds_read_b128 v[234:237], v176 offset:32
	ds_read_b128 v[238:241], v176
	s_waitcnt lgkmcnt(3)
	v_pk_mul_f32 v[18:19], v[18:19], v[222:223]
	s_waitcnt lgkmcnt(2)
	v_pk_mul_f32 v[14:15], v[14:15], v[226:227]
	s_waitcnt lgkmcnt(1)
	v_pk_mul_f32 v[10:11], v[10:11], v[236:237]
	s_waitcnt lgkmcnt(0)
	v_pk_mul_f32 v[6:7], v[6:7], v[240:241]
	v_pk_mul_f32 v[16:17], v[16:17], v[220:221]
	v_pk_mul_f32 v[12:13], v[12:13], v[224:225]
	v_pk_mul_f32 v[8:9], v[8:9], v[234:235]
	v_pk_mul_f32 v[4:5], v[4:5], v[238:239]
	v_pk_mul_f32 v[66:67], v[66:67], v[222:223]
	v_pk_mul_f32 v[62:63], v[62:63], v[226:227]
	v_pk_mul_f32 v[58:59], v[58:59], v[236:237]
	v_pk_mul_f32 v[54:55], v[54:55], v[240:241]
	v_pk_mul_f32 v[64:65], v[64:65], v[220:221]
	v_pk_mul_f32 v[60:61], v[60:61], v[224:225]
	v_pk_mul_f32 v[56:57], v[56:57], v[234:235]
	v_pk_mul_f32 v[52:53], v[52:53], v[238:239]
	v_pk_mul_f32 v[50:51], v[50:51], v[222:223]
	v_pk_mul_f32 v[46:47], v[46:47], v[226:227]
	v_pk_mul_f32 v[42:43], v[42:43], v[236:237]
	v_pk_mul_f32 v[38:39], v[38:39], v[240:241]
	v_pk_mul_f32 v[48:49], v[48:49], v[220:221]
	v_pk_mul_f32 v[44:45], v[44:45], v[224:225]
	v_pk_mul_f32 v[40:41], v[40:41], v[234:235]
	v_pk_mul_f32 v[36:37], v[36:37], v[238:239]
	v_pk_mul_f32 v[34:35], v[34:35], v[222:223]
	v_pk_mul_f32 v[30:31], v[30:31], v[226:227]
	v_pk_mul_f32 v[26:27], v[26:27], v[236:237]
	v_pk_mul_f32 v[22:23], v[22:23], v[240:241]
	v_pk_mul_f32 v[32:33], v[32:33], v[220:221]
	v_pk_mul_f32 v[28:29], v[28:29], v[224:225]
	v_pk_mul_f32 v[24:25], v[24:25], v[234:235]
	v_pk_mul_f32 v[20:21], v[20:21], v[238:239]
